# more transposes tiles moved from P0b into idle blocks: out-proj phase of layer 0 (448 blocks x 4) added, pre-norm phase raised to 8 tiles per idle block
# speedup vs baseline: 1.0103x; 1.0014x over previous
; __device__ __forceinline__ TrJob tr_decode(const Params& p, char* ws, int job) {
;   TrJob t;
;   int l = job / TJ_PER_LAYER, rj = job % TJ_PER_LAYER;
;   if (rj < 640) {
;     t.src = p.w_in + (size_t)l * 1024 * 2560; t.K = 1024; t.N = 2560; t.kt = rj / 40; t.nt = rj % 40;
;     t.dst = (u16*)(ws + OFF_WINT) + (size_t)l * 2560 * 1024; t.mode = 0;
;   } else if (rj < 896) {
;     rj -= 640;
;     t.src = p.w_out + (size_t)l * 1024 * 1024; t.K = 1024; t.N = 1024; t.kt = rj / 16; t.nt = rj % 16;
;     t.dst = (u16*)(ws + OFF_WOUTT) + (size_t)l * 1024 * 1024; t.mode = 0;
;   } else {
;     rj -= 896;
;     int e = rj / 1536, q = rj % 1536;
;     size_t eo = (size_t)(l * 16 + e);
;     if (q < 512) {
;       t.src = p.w_gate + eo * 1024 * 2048; t.K = 1024; t.N = 2048; t.kt = q / 32; t.nt = q % 32;
;       t.dst = (u16*)(ws + OFF_WGUT) + eo * 4096 * 1024; t.mode = 1;
;     } else if (q < 1024) {
;       q -= 512;
;       t.src = p.w_up + eo * 1024 * 2048; t.K = 1024; t.N = 2048; t.kt = q / 32; t.nt = q % 32;
;       t.dst = (u16*)(ws + OFF_WGUT) + eo * 4096 * 1024; t.mode = 2;
;     } else {
;       q -= 1024;
;       t.src = p.w_down + eo * 2048 * 1024; t.K = 2048; t.N = 1024; t.kt = q / 16; t.nt = q % 16;
;       t.dst = (u16*)(ws + OFF_WDT) + eo * 1024 * 2048; t.mode = 0;
;     }
;   }
; __device__ __forceinline__ void p0_transposes(const Params& p, char* smem, int bid, int nb, int jlo, int jhi) {
;     ...
;   for (; j < jhi; j += 2 * nb) {
;     const int jn = j + 2 * nb;
;     if (jn < jhi) { tr_load(p, ws, jn, tid, n0); tr_load(p, ws, jn + 1, tid, n1); }
.LBB0_174:
	s_add_i32 s96, s97, s75
	s_cmp_gt_i32 s96, 0x7bbf
	s_cselect_b64 s[0:1], -1, 0
	s_and_b64 vcc, exec, s[0:1]
	s_cbranch_vccnz .LBB0_208
	s_mul_hi_i32 s10, s96, 0x5254e78f
	s_lshr_b32 s11, s10, 31
	s_ashr_i32 s10, s10, 13
	s_add_i32 s52, s10, s11
	s_mul_i32 s10, s52, 0xffff9c80
	s_add_i32 s10, s96, s10
	s_cmpk_gt_i32 s10, 0x27f
	s_mov_b64 s[58:59], -1
	s_cbranch_scc0 .LBB0_189
	s_cmpk_gt_u32 s10, 0x37f
	s_cbranch_scc0 .LBB0_186
	s_add_i32 s11, s10, 0xfc80
	s_and_b32 s33, s11, 0xffff
	s_mul_i32 s33, s33, 0xaaab
	s_lshr_b32 s33, s33, 26
	s_mul_i32 s40, s33, 0x600
	s_sub_i32 s11, s11, s40
	s_and_b32 s40, s11, 0xffff
	s_lshl_b32 s11, s52, 4
	s_add_i32 s54, s11, s33
	s_ashr_i32 s55, s54, 31
	s_lshl_b64 s[58:59], s[54:55], 23
	s_cmpk_gt_u32 s40, 0x1ff
	s_mov_b64 s[60:61], -1
	s_cbranch_scc0 .LBB0_183
	s_cmpk_gt_u32 s40, 0x3ff
	s_mov_b64 s[56:57], -1
	s_cbranch_scc0 .LBB0_180
	v_readlane_b32 s12, v238, 25
	s_add_i32 s11, s40, 0xfffffc00
	v_readlane_b32 s18, v238, 31
	v_readlane_b32 s19, v238, 32
	s_add_u32 s54, s18, s58
	v_readlane_b32 s13, v238, 26
	v_readlane_b32 s14, v238, 27
	v_readlane_b32 s15, v238, 28
	v_readlane_b32 s16, v238, 29
	v_readlane_b32 s17, v238, 30
	s_addc_u32 s55, s19, s59
	s_lshr_b32 s33, s11, 4
	s_and_b32 s11, s40, 15
	s_mov_b64 s[56:57], 0

; #define GSYNC() do { xcd_barrier(xb); if (REP_MASK & 256) xcd_barrier(xb); } while (0)
; #define LAUNDER(v) asm volatile("" : "+s"(v))
; __device__ __forceinline__ int vtid() { int t = threadIdx.x; asm volatile("" : "+v"(t)); return t; }
; __device__ __forceinline__ void p0_transposes(const Params& p, char* smem, int bid, int nb, int jlo, int jhi) {
;   const int tid = vtid();
;   char* ws = p.ws;
;   LAUNDER(ws);
;   float* tileA = (float*)smem;
;   float* tileB = tileA + 64 * 65;
;   float4 c0[4], c1[4], n0[4], n1[4];
;   int j = jlo + bid * 2;
;   if (j < jhi) { tr_load(p, ws, j, tid, c0); tr_load(p, ws, j + 1, tid, c1); }
;   for (; j < jhi; j += 2 * nb) {
; __global__ void __launch_bounds__(256, 2) fwd_megakernel(Params p) {
;     ...
;     for (int rep = 0; rep < NREP(3); ++rep) {
;       const int ntl = 512 + (l == 0 ? 64 : 0);
;       for (int t = bid; t < ntl; t += nb) {
;         int mt = t >> 3, nt = t & 7, ks = -1;
;         if (t >= 512) { int q = t - 512; ks = q & 3; nt = (q >> 2) & 7; mt = 64 + (q >> 5); }
;         outproj_tile(p, smem, l, mt, nt, ks);
;       }
;       GSYNC();
.Ltrp3_check:
	v_readlane_b32 s0, v237, 29
	s_cmp_lg_u32 s0, 0
	s_cbranch_scc0 .LBB0_1223
	v_readlane_b32 s0, v239, 0
	s_cmpk_lt_i32 s0, 64
	s_cbranch_scc1 .LBB0_1223
	v_readlane_b32 s100, v236, 62
	v_readlane_b32 s101, v236, 63
	v_writelane_b32 v255, s64, 0
	v_writelane_b32 v255, s65, 1
	v_writelane_b32 v255, s66, 2
	v_writelane_b32 v255, s67, 3
	v_writelane_b32 v255, s68, 4
	v_writelane_b32 v255, s69, 5
	v_writelane_b32 v255, s70, 6
	v_writelane_b32 v255, s71, 7
	v_writelane_b32 v255, s72, 8
	v_writelane_b32 v255, s73, 9
	v_writelane_b32 v255, s74, 10
	v_writelane_b32 v255, s75, 11
	v_writelane_b32 v255, s76, 12
	v_writelane_b32 v255, s77, 13
	v_writelane_b32 v255, s78, 14
	v_writelane_b32 v255, s79, 15
	v_writelane_b32 v255, s80, 16
	v_writelane_b32 v255, s81, 17
	v_writelane_b32 v255, s82, 18
	v_writelane_b32 v255, s83, 19
	v_writelane_b32 v255, s84, 20
	v_writelane_b32 v255, s85, 21
	v_writelane_b32 v255, s86, 22
	v_writelane_b32 v255, s87, 23
	v_writelane_b32 v255, s88, 24
	v_writelane_b32 v255, s89, 25
	v_writelane_b32 v255, s90, 26
	v_writelane_b32 v255, s91, 27
	v_writelane_b32 v255, s92, 28
	v_writelane_b32 v255, s93, 29
	v_writelane_b32 v255, s94, 30
	v_writelane_b32 v255, s95, 31
	v_writelane_b32 v255, s96, 32
	v_writelane_b32 v255, s97, 33
	v_writelane_b32 v255, s98, 34
	v_writelane_b32 v255, s99, 35
	v_writelane_b32 v255, vcc_lo, 36
	v_writelane_b32 v255, vcc_hi, 37
	s_load_dwordx4 s[64:67], s[100:101], 0x40
	s_load_dwordx4 s[68:71], s[100:101], 0xc8
	s_load_dwordx2 s[72:73], s[100:101], 0xd8
	s_load_dwordx2 s[74:75], s[100:101], 0xe8
	v_and_b32_e32 v241, 15, v172
	v_lshrrev_b32_e32 v242, 4, v172
	v_lshlrev_b32_e32 v241, 4, v241
	v_mul_u32_u24_e32 v243, 0x104, v242
	v_add_u32_e32 v243, v243, v241
	v_and_b32_e32 v246, 7, v172
	v_lshrrev_b32_e32 v245, 3, v172
	v_mul_u32_u24_e32 v244, 0x820, v246
	v_lshl_add_u32 v244, v245, 2, v244
	v_lshlrev_b32_e32 v246, 4, v246
	v_readlane_b32 s76, v239, 0
	s_add_u32 s76, s76, 31616
	s_movk_i32 s77, 2
	s_mov_b32 s96, 0
	s_waitcnt lgkmcnt(0)
.Ltrp3_batch:
	s_min_u32 s78, s76, 33471
	s_cmp_ge_u32 s78, 25472
	s_cselect_b32 s79, 1, 0
	s_cselect_b32 s85, 25472, 0
	s_sub_u32 s78, s78, s85
	s_cmp_lt_u32 s78, 640
	s_cbranch_scc0 .Ltr_p3l0_notin
	s_mul_hi_u32 s80, s78, 107374183
	s_mul_i32 s85, s80, 40
	s_sub_u32 s81, s78, s85
	s_movk_i32 s82, 2560
	s_movk_i32 s83, 1024
	s_mov_b32 s84, -1
	s_mul_i32 s85, s79, 10485760
	s_add_u32 s86, s64, s85
	s_addc_u32 s87, s65, 0
	s_mul_i32 s85, s79, 5242880
	s_add_u32 s88, s74, s85
	s_addc_u32 s89, s75, 0
	s_branch .Ltr_p3l0_dec_done

; __device__ __forceinline__ TrJob tr_decode(const Params& p, char* ws, int job) {
;   TrJob t;
;   int l = job / TJ_PER_LAYER, rj = job % TJ_PER_LAYER;
;   if (rj < 640) {
;     t.src = p.w_in + (size_t)l * 1024 * 2560; t.K = 1024; t.N = 2560; t.kt = rj / 40; t.nt = rj % 40;
;     t.dst = (u16*)(ws + OFF_WINT) + (size_t)l * 2560 * 1024; t.mode = 0;
; __device__ __forceinline__ void tr_load(const Params& p, char* ws, int job, int tid, float4 (&r)[4]) {
;   TrJob t = tr_decode(p, ws, job);
;   const int c4 = tid & 15, rr = tid >> 4;
;   const float* s0 = t.src + (size_t)(t.kt * 64 + rr) * t.N + t.nt * 64 + c4 * 4;
; #pragma unroll
;   for (int pp = 0; pp < 4; ++pp) {
;     f32x4 v_ = __builtin_nontemporal_load((const f32x4*)(s0 + (size_t)(16 * pp) * t.N));
;     r[pp] = make_float4(v_[0], v_[1], v_[2], v_[3]);
;   }
; }
.Ltr_p3l0_dec_done:
	s_mul_i32 s85, s80, s82
	s_lshl_b32 s85, s85, 8
	s_lshl_b32 s79, s81, 8
	s_add_u32 s85, s85, s79
	s_add_u32 s90, s86, s85
	s_addc_u32 s91, s87, 0
	s_lshl_b32 s92, s82, 2
	s_lshl_b32 s93, s82, 6
	v_mad_u32_u24 v240, v242, s92, v241
	global_load_dwordx4 v[212:215], v240, s[90:91] nt
	v_add_u32_e32 v211, s93, v240
	global_load_dwordx4 v[216:219], v211, s[90:91] nt
	v_add_u32_e32 v240, s93, v211
	global_load_dwordx4 v[220:223], v240, s[90:91] nt
	v_add_u32_e32 v211, s93, v240
	global_load_dwordx4 v[224:227], v211, s[90:91] nt
	s_add_u32 s76, s76, 448
	s_min_u32 s78, s76, 33471
	s_cmp_ge_u32 s78, 25472
	s_cselect_b32 s79, 1, 0
	s_cselect_b32 s85, 25472, 0
	s_sub_u32 s78, s78, s85
	s_cmp_lt_u32 s78, 640
	s_cbranch_scc0 .Ltr_p3l1_notin
	s_mul_hi_u32 s80, s78, 107374183
	s_mul_i32 s85, s80, 40
	s_sub_u32 s81, s78, s85
	s_movk_i32 s82, 2560
	s_movk_i32 s83, 1024
	s_mov_b32 s84, -1
	s_mul_i32 s85, s79, 10485760
	s_add_u32 s86, s64, s85
	s_addc_u32 s87, s65, 0
	s_mul_i32 s85, s79, 5242880
	s_add_u32 s88, s74, s85
	s_addc_u32 s89, s75, 0
	s_branch .Ltr_p3l1_dec_done

; __device__ __forceinline__ void tr_load(const Params& p, char* ws, int job, int tid, float4 (&r)[4]) {
;   TrJob t = tr_decode(p, ws, job);
;   const int c4 = tid & 15, rr = tid >> 4;
;   const float* s0 = t.src + (size_t)(t.kt * 64 + rr) * t.N + t.nt * 64 + c4 * 4;
; #pragma unroll
;   for (int pp = 0; pp < 4; ++pp) {
;     f32x4 v_ = __builtin_nontemporal_load((const f32x4*)(s0 + (size_t)(16 * pp) * t.N));
;     r[pp] = make_float4(v_[0], v_[1], v_[2], v_[3]);
;   }
; }
; __device__ __forceinline__ void tr_lds_write(float* tile, int tid, const float4 (&r)[4]) {
;   const int c4 = tid & 15, rr = tid >> 4;
; #pragma unroll
;   for (int pp = 0; pp < 4; ++pp) {
;     float* t = &tile[(rr + 16 * pp) * 65 + c4 * 4];
;     t[0] = r[pp].x; t[1] = r[pp].y; t[2] = r[pp].z; t[3] = r[pp].w;
;   }
; }
; __device__ __forceinline__ void tr_store(const Params& p, char* ws, int job, int tid, const float* tile) {
;   TrJob t = tr_decode(p, ws, job);
;   const int kc = tid & 7, nn = tid >> 3;
; #pragma unroll
;   for (int pp = 0; pp < 2; ++pp) {
;     int n = nn + 32 * pp;
;     float v[8];
; #pragma unroll
;     for (int j = 0; j < 8; ++j) v[j] = tile[(kc * 8 + j) * 65 + n];
.Ltr_p3l1_dec_done:
	s_mul_i32 s85, s80, s82
	s_lshl_b32 s85, s85, 8
	s_lshl_b32 s79, s81, 8
	s_add_u32 s85, s85, s79
	s_add_u32 s90, s86, s85
	s_addc_u32 s91, s87, 0
	s_lshl_b32 s92, s82, 2
	s_lshl_b32 s93, s82, 6
	v_mad_u32_u24 v240, v242, s92, v241
	global_load_dwordx4 v[228:231], v240, s[90:91] nt
	v_add_u32_e32 v211, s93, v240
	global_load_dwordx4 v[232:235], v211, s[90:91] nt
	v_add_u32_e32 v240, s93, v211
	global_load_dwordx4 v[186:189], v240, s[90:91] nt
	v_add_u32_e32 v211, s93, v240
	global_load_dwordx4 v[190:193], v211, s[90:91] nt
	s_add_u32 s76, s76, 448
	s_sub_u32 s76, s76, 896
	s_waitcnt vmcnt(0)
	v_add_u32_e32 v247, s96, v243
	ds_write_b32 v247, v212 offset:0
	ds_write_b32 v247, v213 offset:4
	ds_write_b32 v247, v214 offset:8
	ds_write_b32 v247, v215 offset:12
	ds_write_b32 v247, v216 offset:4160
	ds_write_b32 v247, v217 offset:4164
	ds_write_b32 v247, v218 offset:4168
	ds_write_b32 v247, v219 offset:4172
	ds_write_b32 v247, v220 offset:8320
	ds_write_b32 v247, v221 offset:8324
	ds_write_b32 v247, v222 offset:8328
	ds_write_b32 v247, v223 offset:8332
	ds_write_b32 v247, v224 offset:12480
	ds_write_b32 v247, v225 offset:12484
	ds_write_b32 v247, v226 offset:12488
	ds_write_b32 v247, v227 offset:12492
	v_add_u32_e32 v247, s96, v244
	s_waitcnt lgkmcnt(0)
	s_barrier
	ds_read_b32 v212, v247 offset:0
	ds_read_b32 v213, v247 offset:260
	ds_read_b32 v214, v247 offset:520
	ds_read_b32 v215, v247 offset:780
	ds_read_b32 v216, v247 offset:1040
	ds_read_b32 v217, v247 offset:1300
	ds_read_b32 v218, v247 offset:1560
	ds_read_b32 v219, v247 offset:1820
	ds_read_b32 v220, v247 offset:128
	ds_read_b32 v221, v247 offset:388
	ds_read_b32 v222, v247 offset:648
	ds_read_b32 v223, v247 offset:908
	ds_read_b32 v224, v247 offset:1168
	ds_read_b32 v225, v247 offset:1428
	ds_read_b32 v226, v247 offset:1688
	ds_read_b32 v227, v247 offset:1948
	s_min_u32 s78, s76, 33471
	s_cmp_ge_u32 s78, 25472
	s_cselect_b32 s79, 1, 0
	s_cselect_b32 s85, 25472, 0
	s_sub_u32 s78, s78, s85
	s_cmp_lt_u32 s78, 640
	s_cbranch_scc0 .Ltr_p3s0_notin
	s_mul_hi_u32 s80, s78, 107374183
	s_mul_i32 s85, s80, 40
	s_sub_u32 s81, s78, s85
	s_movk_i32 s82, 2560
	s_movk_i32 s83, 1024
	s_mov_b32 s84, -1
	s_mul_i32 s85, s79, 10485760
	s_add_u32 s86, s64, s85
	s_addc_u32 s87, s65, 0
	s_mul_i32 s85, s79, 5242880
	s_add_u32 s88, s74, s85
	s_addc_u32 s89, s75, 0
	s_branch .Ltr_p3s0_dec_done

; __device__ __forceinline__ unsigned pack2(float a, float b) { return (unsigned)f2bf(a) | ((unsigned)f2bf(b) << 16); }
; __device__ __forceinline__ void tr_lds_write(float* tile, int tid, const float4 (&r)[4]) {
;   const int c4 = tid & 15, rr = tid >> 4;
; #pragma unroll
;   for (int pp = 0; pp < 4; ++pp) {
;     float* t = &tile[(rr + 16 * pp) * 65 + c4 * 4];
;     t[0] = r[pp].x; t[1] = r[pp].y; t[2] = r[pp].z; t[3] = r[pp].w;
;   }
; }
; __device__ __forceinline__ void tr_store(const Params& p, char* ws, int job, int tid, const float* tile) {
;   TrJob t = tr_decode(p, ws, job);
;   const int kc = tid & 7, nn = tid >> 3;
; #pragma unroll
;   for (int pp = 0; pp < 2; ++pp) {
;     int n = nn + 32 * pp;
;     float v[8];
; #pragma unroll
;     for (int j = 0; j < 8; ++j) v[j] = tile[(kc * 8 + j) * 65 + n];
;     uint4 o;
;     o.x = pack2(v[0], v[1]); o.y = pack2(v[2], v[3]); o.z = pack2(v[4], v[5]); o.w = pack2(v[6], v[7]);
;     int gn = t.nt * 64 + n;
;     int drow = t.mode == 0 ? gn : gu_row(t.mode - 1, gn);
;     *(uint4*)&t.dst[(size_t)drow * t.K + t.kt * 64 + kc * 8] = o;
;   }
; }
.Ltr_p3s0_dec_done:
	s_lshl_b32 s97, s83, 1
	s_cmp_eq_u32 s84, -1
	s_cselect_b32 s79, 6, 7
	s_cselect_b32 s85, 32, 64
	s_cselect_b32 s78, 0, s84
	s_lshl_b32 s79, s81, s79
	s_add_u32 s79, s79, s78
	s_add_u32 s85, s85, s79
	s_mul_i32 s79, s79, s97
	s_mul_i32 s85, s85, s97
	s_lshl_b32 s78, s80, 7
	s_add_u32 s79, s79, s78
	s_add_u32 s85, s85, s78
	s_add_u32 s94, s88, s79
	s_addc_u32 s95, s89, 0
	s_add_u32 s98, s88, s85
	s_addc_u32 s99, s89, 0
	v_mad_u32_u24 v254, v245, s97, v246
	s_movk_i32 s78, 0x7fff
	s_mov_b32 s79, 0xffff0000
	s_waitcnt lgkmcnt(0)
	v_bfe_u32 v252, v212, 16, 1
	v_bfe_u32 v253, v213, 16, 1
	v_add3_u32 v252, v212, v252, s78
	v_add3_u32 v253, v213, v253, s78
	v_lshrrev_b32_e32 v252, 16, v252
	v_and_or_b32 v248, v253, s79, v252
	v_bfe_u32 v252, v214, 16, 1
	v_bfe_u32 v253, v215, 16, 1
	v_add3_u32 v252, v214, v252, s78
	v_add3_u32 v253, v215, v253, s78
	v_lshrrev_b32_e32 v252, 16, v252
	v_and_or_b32 v249, v253, s79, v252
	v_bfe_u32 v252, v216, 16, 1
	v_bfe_u32 v253, v217, 16, 1
	v_add3_u32 v252, v216, v252, s78
	v_add3_u32 v253, v217, v253, s78
	v_lshrrev_b32_e32 v252, 16, v252
	v_and_or_b32 v250, v253, s79, v252
	v_bfe_u32 v252, v218, 16, 1
	v_bfe_u32 v253, v219, 16, 1
	v_add3_u32 v252, v218, v252, s78
	v_add3_u32 v253, v219, v253, s78
	v_lshrrev_b32_e32 v252, 16, v252
	v_and_or_b32 v251, v253, s79, v252
	global_store_dwordx4 v254, v[248:251], s[94:95]
	s_nop 1
	v_bfe_u32 v252, v220, 16, 1
	v_bfe_u32 v253, v221, 16, 1
	v_add3_u32 v252, v220, v252, s78
	v_add3_u32 v253, v221, v253, s78
	v_lshrrev_b32_e32 v252, 16, v252
	v_and_or_b32 v248, v253, s79, v252
	v_bfe_u32 v252, v222, 16, 1
	v_bfe_u32 v253, v223, 16, 1
	v_add3_u32 v252, v222, v252, s78
	v_add3_u32 v253, v223, v253, s78
	v_lshrrev_b32_e32 v252, 16, v252
	v_and_or_b32 v249, v253, s79, v252
	v_bfe_u32 v252, v224, 16, 1
	v_bfe_u32 v253, v225, 16, 1
	v_add3_u32 v252, v224, v252, s78
	v_add3_u32 v253, v225, v253, s78
	v_lshrrev_b32_e32 v252, 16, v252
	v_and_or_b32 v250, v253, s79, v252
	v_bfe_u32 v252, v226, 16, 1
	v_bfe_u32 v253, v227, 16, 1
	v_add3_u32 v252, v226, v252, s78
	v_add3_u32 v253, v227, v253, s78
	v_lshrrev_b32_e32 v252, 16, v252
	v_and_or_b32 v251, v253, s79, v252
	global_store_dwordx4 v254, v[248:251], s[98:99]
	s_xor_b32 s96, s96, 0x4100
	s_add_u32 s76, s76, 448
	v_add_u32_e32 v247, s96, v243
	ds_write_b32 v247, v228 offset:0
	ds_write_b32 v247, v229 offset:4
	ds_write_b32 v247, v230 offset:8
	ds_write_b32 v247, v231 offset:12
	ds_write_b32 v247, v232 offset:4160
	ds_write_b32 v247, v233 offset:4164
	ds_write_b32 v247, v234 offset:4168
	ds_write_b32 v247, v235 offset:4172
	ds_write_b32 v247, v186 offset:8320
	ds_write_b32 v247, v187 offset:8324
	ds_write_b32 v247, v188 offset:8328
	ds_write_b32 v247, v189 offset:8332
	ds_write_b32 v247, v190 offset:12480
	ds_write_b32 v247, v191 offset:12484
	ds_write_b32 v247, v192 offset:12488
	ds_write_b32 v247, v193 offset:12492
	v_add_u32_e32 v247, s96, v244
	s_waitcnt lgkmcnt(0)
	s_barrier
	ds_read_b32 v228, v247 offset:0
	ds_read_b32 v229, v247 offset:260
	ds_read_b32 v230, v247 offset:520
	ds_read_b32 v231, v247 offset:780
	ds_read_b32 v232, v247 offset:1040
	ds_read_b32 v233, v247 offset:1300
	ds_read_b32 v234, v247 offset:1560
	ds_read_b32 v235, v247 offset:1820
	ds_read_b32 v186, v247 offset:128
	ds_read_b32 v187, v247 offset:388
	ds_read_b32 v188, v247 offset:648
	ds_read_b32 v189, v247 offset:908
	ds_read_b32 v190, v247 offset:1168
	ds_read_b32 v191, v247 offset:1428
	ds_read_b32 v192, v247 offset:1688
	ds_read_b32 v193, v247 offset:1948
	s_min_u32 s78, s76, 33471
	s_cmp_ge_u32 s78, 25472
	s_cselect_b32 s79, 1, 0
	s_cselect_b32 s85, 25472, 0
	s_sub_u32 s78, s78, s85
	s_cmp_lt_u32 s78, 640
	s_cbranch_scc0 .Ltr_p3s1_notin
	s_mul_hi_u32 s80, s78, 107374183
	s_mul_i32 s85, s80, 40
	s_sub_u32 s81, s78, s85
	s_movk_i32 s82, 2560
	s_movk_i32 s83, 1024
	s_mov_b32 s84, -1
	s_mul_i32 s85, s79, 10485760
	s_add_u32 s86, s64, s85
	s_addc_u32 s87, s65, 0
	s_mul_i32 s85, s79, 5242880
	s_add_u32 s88, s74, s85
	s_addc_u32 s89, s75, 0
	s_branch .Ltr_p3s1_dec_done

; __device__ __forceinline__ unsigned pack2(float a, float b) { return (unsigned)f2bf(a) | ((unsigned)f2bf(b) << 16); }
; __device__ __forceinline__ void xcd_barrier(const XcdBarrier& b) {
;   asm volatile("s_waitcnt vmcnt(0)" ::: "memory");
;   __syncthreads();
;   if (threadIdx.x == 0) {
;     unsigned* bar = b.bar;
;     __builtin_amdgcn_s_waitcnt(0);
;     unsigned nloc = b.st[0], nx = b.st[1];
;     if (nloc == 0u) { xcd_barrier_complete(bar, b.x, nloc, nx); b.st[0] = nloc; b.st[1] = nx; }
; __device__ __forceinline__ void tr_store(const Params& p, char* ws, int job, int tid, const float* tile) {
;   TrJob t = tr_decode(p, ws, job);
;   const int kc = tid & 7, nn = tid >> 3;
; #pragma unroll
;   for (int pp = 0; pp < 2; ++pp) {
;     int n = nn + 32 * pp;
;     float v[8];
; #pragma unroll
;     for (int j = 0; j < 8; ++j) v[j] = tile[(kc * 8 + j) * 65 + n];
;     uint4 o;
;     o.x = pack2(v[0], v[1]); o.y = pack2(v[2], v[3]); o.z = pack2(v[4], v[5]); o.w = pack2(v[6], v[7]);
;     int gn = t.nt * 64 + n;
;     int drow = t.mode == 0 ? gn : gu_row(t.mode - 1, gn);
;     *(uint4*)&t.dst[(size_t)drow * t.K + t.kt * 64 + kc * 8] = o;
;   }
; }
.Ltr_p3s1_dec_done:
	s_lshl_b32 s97, s83, 1
	s_cmp_eq_u32 s84, -1
	s_cselect_b32 s79, 6, 7
	s_cselect_b32 s85, 32, 64
	s_cselect_b32 s78, 0, s84
	s_lshl_b32 s79, s81, s79
	s_add_u32 s79, s79, s78
	s_add_u32 s85, s85, s79
	s_mul_i32 s79, s79, s97
	s_mul_i32 s85, s85, s97
	s_lshl_b32 s78, s80, 7
	s_add_u32 s79, s79, s78
	s_add_u32 s85, s85, s78
	s_add_u32 s94, s88, s79
	s_addc_u32 s95, s89, 0
	s_add_u32 s98, s88, s85
	s_addc_u32 s99, s89, 0
	v_mad_u32_u24 v254, v245, s97, v246
	s_movk_i32 s78, 0x7fff
	s_mov_b32 s79, 0xffff0000
	s_waitcnt lgkmcnt(0)
	v_bfe_u32 v252, v228, 16, 1
	v_bfe_u32 v253, v229, 16, 1
	v_add3_u32 v252, v228, v252, s78
	v_add3_u32 v253, v229, v253, s78
	v_lshrrev_b32_e32 v252, 16, v252
	v_and_or_b32 v248, v253, s79, v252
	v_bfe_u32 v252, v230, 16, 1
	v_bfe_u32 v253, v231, 16, 1
	v_add3_u32 v252, v230, v252, s78
	v_add3_u32 v253, v231, v253, s78
	v_lshrrev_b32_e32 v252, 16, v252
	v_and_or_b32 v249, v253, s79, v252
	v_bfe_u32 v252, v232, 16, 1
	v_bfe_u32 v253, v233, 16, 1
	v_add3_u32 v252, v232, v252, s78
	v_add3_u32 v253, v233, v253, s78
	v_lshrrev_b32_e32 v252, 16, v252
	v_and_or_b32 v250, v253, s79, v252
	v_bfe_u32 v252, v234, 16, 1
	v_bfe_u32 v253, v235, 16, 1
	v_add3_u32 v252, v234, v252, s78
	v_add3_u32 v253, v235, v253, s78
	v_lshrrev_b32_e32 v252, 16, v252
	v_and_or_b32 v251, v253, s79, v252
	global_store_dwordx4 v254, v[248:251], s[94:95]
	s_nop 1
	v_bfe_u32 v252, v186, 16, 1
	v_bfe_u32 v253, v187, 16, 1
	v_add3_u32 v252, v186, v252, s78
	v_add3_u32 v253, v187, v253, s78
	v_lshrrev_b32_e32 v252, 16, v252
	v_and_or_b32 v248, v253, s79, v252
	v_bfe_u32 v252, v188, 16, 1
	v_bfe_u32 v253, v189, 16, 1
	v_add3_u32 v252, v188, v252, s78
	v_add3_u32 v253, v189, v253, s78
	v_lshrrev_b32_e32 v252, 16, v252
	v_and_or_b32 v249, v253, s79, v252
	v_bfe_u32 v252, v190, 16, 1
	v_bfe_u32 v253, v191, 16, 1
	v_add3_u32 v252, v190, v252, s78
	v_add3_u32 v253, v191, v253, s78
	v_lshrrev_b32_e32 v252, 16, v252
	v_and_or_b32 v250, v253, s79, v252
	v_bfe_u32 v252, v192, 16, 1
	v_bfe_u32 v253, v193, 16, 1
	v_add3_u32 v252, v192, v252, s78
	v_add3_u32 v253, v193, v253, s78
	v_lshrrev_b32_e32 v252, 16, v252
	v_and_or_b32 v251, v253, s79, v252
	global_store_dwordx4 v254, v[248:251], s[98:99]
	s_xor_b32 s96, s96, 0x4100
	s_add_u32 s76, s76, 448
	s_sub_u32 s77, s77, 1
	s_cmp_lg_u32 s77, 0
	s_cbranch_scc1 .Ltrp3_batch
	s_waitcnt vmcnt(0) lgkmcnt(0)
	s_barrier
	v_readlane_b32 s64, v255, 0
	v_readlane_b32 s65, v255, 1
	v_readlane_b32 s66, v255, 2
	v_readlane_b32 s67, v255, 3
	v_readlane_b32 s68, v255, 4
	v_readlane_b32 s69, v255, 5
	v_readlane_b32 s70, v255, 6
	v_readlane_b32 s71, v255, 7
	v_readlane_b32 s72, v255, 8
	v_readlane_b32 s73, v255, 9
	v_readlane_b32 s74, v255, 10
	v_readlane_b32 s75, v255, 11
	v_readlane_b32 s76, v255, 12
	v_readlane_b32 s77, v255, 13
	v_readlane_b32 s78, v255, 14
	v_readlane_b32 s79, v255, 15
	v_readlane_b32 s80, v255, 16
	v_readlane_b32 s81, v255, 17
	v_readlane_b32 s82, v255, 18
	v_readlane_b32 s83, v255, 19
	v_readlane_b32 s84, v255, 20
	v_readlane_b32 s85, v255, 21
	v_readlane_b32 s86, v255, 22
	v_readlane_b32 s87, v255, 23
	v_readlane_b32 s88, v255, 24
	v_readlane_b32 s89, v255, 25
	v_readlane_b32 s90, v255, 26
	v_readlane_b32 s91, v255, 27
	v_readlane_b32 s92, v255, 28
	v_readlane_b32 s93, v255, 29
	v_readlane_b32 s94, v255, 30
	v_readlane_b32 s95, v255, 31
	v_readlane_b32 s96, v255, 32
	v_readlane_b32 s97, v255, 33
	v_readlane_b32 s98, v255, 34
	v_readlane_b32 s99, v255, 35
	v_readlane_b32 vcc_lo, v255, 36
	v_readlane_b32 vcc_hi, v255, 37
	s_nop 4
.LBB0_1223:
	s_waitcnt vmcnt(0)
	s_barrier
	s_and_saveexec_b64 s[0:1], s[96:97]
	s_cbranch_execz .LBB0_1267
	s_waitcnt vmcnt(0) expcnt(0) lgkmcnt(0)
	ds_read_b32 v2, v1 offset:65472
	ds_read_b32 v0, v1 offset:65476
	s_waitcnt lgkmcnt(1)
	v_cmp_ne_u32_e32 vcc, 0, v2
	s_cbranch_vccnz .LBB0_1238
	s_mov_b32 s2, 1
	s_mov_b64 s[4:5], 0
	s_branch .LBB0_1228

; #define GSYNC() do { xcd_barrier(xb); if (REP_MASK & 256) xcd_barrier(xb); } while (0)
; #define LAUNDER(v) asm volatile("" : "+s"(v))
; __device__ __forceinline__ int vtid() { int t = threadIdx.x; asm volatile("" : "+v"(t)); return t; }
; __device__ __forceinline__ void p0_transposes(const Params& p, char* smem, int bid, int nb, int jlo, int jhi) {
;   const int tid = vtid();
;   char* ws = p.ws;
;   LAUNDER(ws);
;   float* tileA = (float*)smem;
;   float* tileB = tileA + 64 * 65;
;   float4 c0[4], c1[4], n0[4], n1[4];
;   int j = jlo + bid * 2;
;   if (j < jhi) { tr_load(p, ws, j, tid, c0); tr_load(p, ws, j + 1, tid, c1); }
;   for (; j < jhi; j += 2 * nb) {
; __global__ void __launch_bounds__(256, 2) fwd_megakernel(Params p) {
;     ...
;     if (l == 0) {
;       for (int job = bid; job < 264; job += nb) norm_job(p, 1, job, false);
;       GSYNC();
.LBB0_2017:
	v_readlane_b32 s0, v237, 25
	v_readlane_b32 s1, v237, 26
	s_andn2_b64 vcc, exec, s[0:1]
	v_readlane_b32 s0, v238, 37
	v_readlane_b32 s2, v239, 0
	s_cbranch_vccz .LBB0_2022
	v_readlane_b32 s100, v236, 62
	v_readlane_b32 s101, v236, 63
	v_writelane_b32 v255, s64, 0
	v_writelane_b32 v255, s65, 1
	v_writelane_b32 v255, s66, 2
	v_writelane_b32 v255, s67, 3
	v_writelane_b32 v255, s68, 4
	v_writelane_b32 v255, s69, 5
	v_writelane_b32 v255, s70, 6
	v_writelane_b32 v255, s71, 7
	v_writelane_b32 v255, s72, 8
	v_writelane_b32 v255, s73, 9
	v_writelane_b32 v255, s74, 10
	v_writelane_b32 v255, s75, 11
	v_writelane_b32 v255, s76, 12
	v_writelane_b32 v255, s77, 13
	v_writelane_b32 v255, s78, 14
	v_writelane_b32 v255, s79, 15
	v_writelane_b32 v255, s80, 16
	v_writelane_b32 v255, s81, 17
	v_writelane_b32 v255, s82, 18
	v_writelane_b32 v255, s83, 19
	v_writelane_b32 v255, s84, 20
	v_writelane_b32 v255, s85, 21
	v_writelane_b32 v255, s86, 22
	v_writelane_b32 v255, s87, 23
	v_writelane_b32 v255, s88, 24
	v_writelane_b32 v255, s89, 25
	v_writelane_b32 v255, s90, 26
	v_writelane_b32 v255, s91, 27
	v_writelane_b32 v255, s92, 28
	v_writelane_b32 v255, s93, 29
	v_writelane_b32 v255, s94, 30
	v_writelane_b32 v255, s95, 31
	v_writelane_b32 v255, s96, 32
	v_writelane_b32 v255, s97, 33
	v_writelane_b32 v255, s98, 34
	v_writelane_b32 v255, s99, 35
	v_writelane_b32 v255, vcc_lo, 36
	v_writelane_b32 v255, vcc_hi, 37
	s_load_dwordx4 s[64:67], s[100:101], 0x40
	s_load_dwordx4 s[68:71], s[100:101], 0xc8
	s_load_dwordx2 s[72:73], s[100:101], 0xd8
	s_load_dwordx2 s[74:75], s[100:101], 0xe8
	v_and_b32_e32 v241, 15, v172
	v_lshrrev_b32_e32 v242, 4, v172
	v_lshlrev_b32_e32 v241, 4, v241
	v_mul_u32_u24_e32 v243, 0x104, v242
	v_add_u32_e32 v243, v243, v241
	v_and_b32_e32 v246, 7, v172
	v_lshrrev_b32_e32 v245, 3, v172
	v_mul_u32_u24_e32 v244, 0x820, v246
	v_lshl_add_u32 v244, v245, 2, v244
	v_lshlrev_b32_e32 v246, 4, v246
	v_readlane_b32 s76, v239, 0
	s_add_u32 s76, s76, 33208
	s_movk_i32 s77, 4
	s_mov_b32 s96, 0
	s_waitcnt lgkmcnt(0)
